# v17 + P6 bf16 main loop LDS-DMA loads in SGPR-base + VGPR-offset form (all six GEMM loops now)
# baseline (speedup 1.0000x reference)
; #define PG8_STAGE(bufoff, gbase, voff) do { _Pragma("unroll") for (int _i = 0; _i < 2; ++_i) \
;         __builtin_amdgcn_global_load_lds((const unsigned*)((const char*)(gbase) + (voff)[_i]), (PG8_LAS unsigned*)(lds + (bufoff) + ldsw + _i * 8192), 16, 0, 0); } while (0)
; #define PG8_LDA(dst, b, h) do { _Pragma("unroll") for (int m = 0; m < 4; ++m) _Pragma("unroll") for (int k = 0; k < 2; ++k) dst[m][k] = *(const PG8_LAS bf16x8*)(lds + PG8_SA(b, h) + aoff + m * 2048 + k * 1024); } while (0)
; #define PG8_LDB(dst, b, h) do { _Pragma("unroll") for (int n = 0; n < 2; ++n) _Pragma("unroll") for (int k = 0; k < 2; ++k) dst[n][k] = *(const PG8_LAS bf16x8*)(lds + PG8_SB(b, h) + boff + n * 2048 + k * 1024); } while (0)
; #define PG8_MMA(ai, bj, At, Bt) do { __builtin_amdgcn_s_setprio(1); _Pragma("unroll") for (int m = 0; m < 4; ++m) _Pragma("unroll") for (int n = 0; n < 2; ++n) _Pragma("unroll") for (int k = 0; k < 2; ++k) \
;         acc[ai][bj][m][n] = __builtin_amdgcn_mfma_f32_16x16x32_bf16(Bt[n][k], At[m][k], acc[ai][bj][m][n], 0, 0, 0); __builtin_amdgcn_s_setprio(0); } while (0)
; #define PG8_WAIT_V(n) asm volatile("s_waitcnt vmcnt(" #n ")" ::: "memory")
; #define PG8_WAIT_L(n) asm volatile("s_waitcnt lgkmcnt(" #n ")" ::: "memory")
; #define PG8_BAR __builtin_amdgcn_s_barrier()
; #define PG8_SCHED __builtin_amdgcn_sched_barrier(0)
; #define PG8_STAGE(bufoff, gbase, voff) do { _Pragma("unroll") for (int _i = 0; _i < 2; ++_i) \
;         __builtin_amdgcn_global_load_lds((const unsigned*)((const char*)(gbase) + (voff)[_i]), (PG8_LAS unsigned*)(lds + (bufoff) + ldsw + _i * 8192), 16, 0, 0); } while (0)
; #define PG8_WAIT_V(n) asm volatile("s_waitcnt vmcnt(" #n ")" ::: "memory")
; template <class Epi, class Sched, bool ALIGN_EPI = false>
; __device__ __forceinline__ void gemm_phase(PG8_LAS unsigned char* lds, const Gemm g, const Sched& S, const Epi& E) {
;     ...
;             PG8_LDB(B0, 0, 0); PG8_LDB(B1, 0, 1); PG8_SCHED; PG8_LDA(At, 0, 0); PG8_STAGE(PG8_SA(1, 1), a1 + hstepA, voffA);
;             PG8_WAIT_V(8); PG8_WAIT_L(0); PG8_BAR; PG8_MMA(0, 0, At, B0); PG8_MMA(0, 1, At, B1); PG8_BAR; PG8_SCHED;
;             PG8_LDA(At, 0, 1); PG8_STAGE(PG8_SB(0, 0), b2, voffB); PG8_STAGE(PG8_SB(0, 1), b2 + hstepB, voffB); PG8_STAGE(PG8_SA(0, 0), a2, voffA);
;             PG8_WAIT_V(8); PG8_WAIT_L(0); PG8_BAR; PG8_MMA(1, 0, At, B0); PG8_MMA(1, 1, At, B1); PG8_BAR; PG8_SCHED;
.LBB0_734:
	ds_read_b128 v[130:133], v165
	ds_read_b128 v[134:137], v165 offset:1024
	ds_read_b128 v[158:161], v165 offset:2048
	ds_read_b128 v[170:173], v165 offset:3072
	ds_read_b128 v[174:177], v166
	ds_read_b128 v[178:181], v166 offset:1024
	ds_read_b128 v[182:185], v166 offset:2048
	ds_read_b128 v[186:189], v166 offset:3072
	s_add_u32 s34, s52, 0xfff80080
	s_addc_u32 s35, s53, -1
	s_cmp_eq_u32 s85, 28
	s_cselect_b32 s55, s13, s35
	s_cselect_b32 s54, s27, s34
	s_cselect_b32 s35, s25, s84
	s_cselect_b32 s34, s82, s83
	s_add_i32 m0, s61, 0xc000
	ds_read_b128 v[190:193], v167
	ds_read_b128 v[194:197], v167 offset:1024
	ds_read_b128 v[198:201], v167 offset:2048
	ds_read_b128 v[202:205], v167 offset:3072
	ds_read_b128 v[206:209], v167 offset:4096
	ds_read_b128 v[210:213], v167 offset:5120
	ds_read_b128 v[214:217], v167 offset:6144
	ds_read_b128 v[218:221], v167 offset:7168
	global_load_lds_dwordx4 v150, s[52:53]
	s_add_i32 m0, s61, 0xe000
	s_nop 0
	global_load_lds_dwordx4 v152, s[52:53]
	s_waitcnt vmcnt(8)
	s_waitcnt lgkmcnt(0)
	s_barrier
	s_waitcnt lgkmcnt(0)
	s_cmp_eq_u32 s100, 1
	s_cbranch_scc1 .Lcy2_0f
	v_mfma_f32_16x16x32_bf16 v[126:129], v[130:133], v[190:193], v[126:129]
	v_mfma_f32_16x16x32_bf16 v[122:125], v[158:161], v[190:193], v[122:125]
	v_mfma_f32_16x16x32_bf16 v[114:117], v[130:133], v[198:201], v[114:117]
	v_mfma_f32_16x16x32_bf16 v[106:109], v[158:161], v[198:201], v[106:109]
	v_mfma_f32_16x16x32_bf16 v[98:101], v[130:133], v[206:209], v[98:101]
	v_mfma_f32_16x16x32_bf16 v[90:93], v[158:161], v[206:209], v[90:93]
	v_mfma_f32_16x16x32_bf16 v[82:85], v[130:133], v[214:217], v[82:85]
	v_mfma_f32_16x16x32_bf16 v[74:77], v[158:161], v[214:217], v[74:77]
	v_mfma_f32_16x16x32_bf16 v[126:129], v[134:137], v[194:197], v[126:129]
	v_mfma_f32_16x16x32_bf16 v[122:125], v[170:173], v[194:197], v[122:125]
	v_mfma_f32_16x16x32_bf16 v[114:117], v[134:137], v[202:205], v[114:117]
	v_mfma_f32_16x16x32_bf16 v[106:109], v[170:173], v[202:205], v[106:109]
	v_mfma_f32_16x16x32_bf16 v[98:101], v[134:137], v[210:213], v[98:101]
	v_mfma_f32_16x16x32_bf16 v[90:93], v[170:173], v[210:213], v[90:93]
	v_mfma_f32_16x16x32_bf16 v[82:85], v[134:137], v[218:221], v[82:85]
	v_mfma_f32_16x16x32_bf16 v[74:77], v[170:173], v[218:221], v[74:77]
	v_mfma_f32_16x16x32_bf16 v[118:121], v[174:177], v[190:193], v[118:121]
	v_mfma_f32_16x16x32_bf16 v[110:113], v[182:185], v[190:193], v[110:113]
	v_mfma_f32_16x16x32_bf16 v[102:105], v[174:177], v[198:201], v[102:105]
	v_mfma_f32_16x16x32_bf16 v[94:97], v[182:185], v[198:201], v[94:97]
	v_mfma_f32_16x16x32_bf16 v[86:89], v[174:177], v[206:209], v[86:89]
	v_mfma_f32_16x16x32_bf16 v[78:81], v[182:185], v[206:209], v[78:81]
	v_mfma_f32_16x16x32_bf16 v[70:73], v[174:177], v[214:217], v[70:73]
	v_mfma_f32_16x16x32_bf16 v[66:69], v[182:185], v[214:217], v[66:69]
	v_mfma_f32_16x16x32_bf16 v[118:121], v[178:181], v[194:197], v[118:121]
	v_mfma_f32_16x16x32_bf16 v[110:113], v[186:189], v[194:197], v[110:113]
	v_mfma_f32_16x16x32_bf16 v[102:105], v[178:181], v[202:205], v[102:105]
	v_mfma_f32_16x16x32_bf16 v[94:97], v[186:189], v[202:205], v[94:97]
	v_mfma_f32_16x16x32_bf16 v[86:89], v[178:181], v[210:213], v[86:89]
	v_mfma_f32_16x16x32_bf16 v[78:81], v[186:189], v[210:213], v[78:81]
	v_mfma_f32_16x16x32_bf16 v[70:73], v[178:181], v[218:221], v[70:73]
	v_mfma_f32_16x16x32_bf16 v[66:69], v[186:189], v[218:221], v[66:69]
.Lcy2_0j:
	s_barrier
	s_add_i32 s88, s72, s58
	s_mov_b32 m0, s88
	ds_read_b128 v[190:193], v167 offset:16384
	ds_read_b128 v[194:197], v167 offset:17408
	ds_read_b128 v[198:201], v167 offset:18432
	ds_read_b128 v[202:205], v167 offset:19456
	ds_read_b128 v[206:209], v167 offset:20480
	ds_read_b128 v[210:213], v167 offset:21504
	ds_read_b128 v[214:217], v167 offset:22528
	ds_read_b128 v[218:221], v167 offset:23552
	global_load_lds_dwordx4 v140, s[34:35]
	s_add_i32 m0, s88, 0x2000
	s_add_u32 s88, s34, 0x80000
	s_addc_u32 s89, s35, 0
	s_add_i32 s90, s73, s58
	global_load_lds_dwordx4 v144, s[34:35]
	s_mov_b32 m0, s90
	s_nop 0
	global_load_lds_dwordx4 v140, s[88:89]
	s_add_i32 m0, s90, 0x2000
	s_nop 0
	global_load_lds_dwordx4 v144, s[88:89]
	s_mov_b32 m0, s61
	s_nop 0
	global_load_lds_dwordx4 v138, s[54:55]
	s_mov_b32 m0, s62
	s_nop 0
	global_load_lds_dwordx4 v142, s[54:55]
	s_waitcnt vmcnt(8)
	s_waitcnt lgkmcnt(0)
	s_barrier
	s_waitcnt lgkmcnt(0)
	s_cmp_eq_u32 s100, 1
	s_cbranch_scc1 .Lcy2_1f
	v_mfma_f32_16x16x32_bf16 v[62:65], v[130:133], v[190:193], v[62:65]
	v_mfma_f32_16x16x32_bf16 v[58:61], v[158:161], v[190:193], v[58:61]
	v_mfma_f32_16x16x32_bf16 v[54:57], v[130:133], v[198:201], v[54:57]
	v_mfma_f32_16x16x32_bf16 v[46:49], v[158:161], v[198:201], v[46:49]
	v_mfma_f32_16x16x32_bf16 v[38:41], v[130:133], v[206:209], v[38:41]
	v_mfma_f32_16x16x32_bf16 v[30:33], v[158:161], v[206:209], v[30:33]
	v_mfma_f32_16x16x32_bf16 v[22:25], v[130:133], v[214:217], v[22:25]
	v_mfma_f32_16x16x32_bf16 v[14:17], v[158:161], v[214:217], v[14:17]
	v_mfma_f32_16x16x32_bf16 v[62:65], v[134:137], v[194:197], v[62:65]
	v_mfma_f32_16x16x32_bf16 v[58:61], v[170:173], v[194:197], v[58:61]
	v_mfma_f32_16x16x32_bf16 v[54:57], v[134:137], v[202:205], v[54:57]
	v_mfma_f32_16x16x32_bf16 v[46:49], v[170:173], v[202:205], v[46:49]
	v_mfma_f32_16x16x32_bf16 v[38:41], v[134:137], v[210:213], v[38:41]
	v_mfma_f32_16x16x32_bf16 v[30:33], v[170:173], v[210:213], v[30:33]
	v_mfma_f32_16x16x32_bf16 v[22:25], v[134:137], v[218:221], v[22:25]
	v_mfma_f32_16x16x32_bf16 v[14:17], v[170:173], v[218:221], v[14:17]
	v_mfma_f32_16x16x32_bf16 v[50:53], v[174:177], v[190:193], v[50:53]
	v_mfma_f32_16x16x32_bf16 v[42:45], v[182:185], v[190:193], v[42:45]
	v_mfma_f32_16x16x32_bf16 v[34:37], v[174:177], v[198:201], v[34:37]
	v_mfma_f32_16x16x32_bf16 v[26:29], v[182:185], v[198:201], v[26:29]
	v_mfma_f32_16x16x32_bf16 v[18:21], v[174:177], v[206:209], v[18:21]
	v_mfma_f32_16x16x32_bf16 v[10:13], v[182:185], v[206:209], v[10:13]
	v_mfma_f32_16x16x32_bf16 v[6:9], v[174:177], v[214:217], v[6:9]
	v_mfma_f32_16x16x32_bf16 v[2:5], v[182:185], v[214:217], v[2:5]
	v_mfma_f32_16x16x32_bf16 v[50:53], v[178:181], v[194:197], v[50:53]
	v_mfma_f32_16x16x32_bf16 v[42:45], v[186:189], v[194:197], v[42:45]
	v_mfma_f32_16x16x32_bf16 v[34:37], v[178:181], v[202:205], v[34:37]
	v_mfma_f32_16x16x32_bf16 v[26:29], v[186:189], v[202:205], v[26:29]
	v_mfma_f32_16x16x32_bf16 v[18:21], v[178:181], v[210:213], v[18:21]
	v_mfma_f32_16x16x32_bf16 v[10:13], v[186:189], v[210:213], v[10:13]
	v_mfma_f32_16x16x32_bf16 v[6:9], v[178:181], v[218:221], v[6:9]
	v_mfma_f32_16x16x32_bf16 v[2:5], v[186:189], v[218:221], v[2:5]
; #define PG8_STAGE(bufoff, gbase, voff) do { _Pragma("unroll") for (int _i = 0; _i < 2; ++_i) \
;         __builtin_amdgcn_global_load_lds((const unsigned*)((const char*)(gbase) + (voff)[_i]), (PG8_LAS unsigned*)(lds + (bufoff) + ldsw + _i * 8192), 16, 0, 0); } while (0)
; #define PG8_LDA(dst, b, h) do { _Pragma("unroll") for (int m = 0; m < 4; ++m) _Pragma("unroll") for (int k = 0; k < 2; ++k) dst[m][k] = *(const PG8_LAS bf16x8*)(lds + PG8_SA(b, h) + aoff + m * 2048 + k * 1024); } while (0)
; #define PG8_LDB(dst, b, h) do { _Pragma("unroll") for (int n = 0; n < 2; ++n) _Pragma("unroll") for (int k = 0; k < 2; ++k) dst[n][k] = *(const PG8_LAS bf16x8*)(lds + PG8_SB(b, h) + boff + n * 2048 + k * 1024); } while (0)
; #define PG8_MMA(ai, bj, At, Bt) do { __builtin_amdgcn_s_setprio(1); _Pragma("unroll") for (int m = 0; m < 4; ++m) _Pragma("unroll") for (int n = 0; n < 2; ++n) _Pragma("unroll") for (int k = 0; k < 2; ++k) \
;         acc[ai][bj][m][n] = __builtin_amdgcn_mfma_f32_16x16x32_bf16(Bt[n][k], At[m][k], acc[ai][bj][m][n], 0, 0, 0); __builtin_amdgcn_s_setprio(0); } while (0)
; #define PG8_WAIT_V(n) asm volatile("s_waitcnt vmcnt(" #n ")" ::: "memory")
; #define PG8_WAIT_L(n) asm volatile("s_waitcnt lgkmcnt(" #n ")" ::: "memory")
; #define PG8_BAR __builtin_amdgcn_s_barrier()
; #define PG8_SCHED __builtin_amdgcn_sched_barrier(0)
; #define PG8_STAGE(bufoff, gbase, voff) do { _Pragma("unroll") for (int _i = 0; _i < 2; ++_i) \
;         __builtin_amdgcn_global_load_lds((const unsigned*)((const char*)(gbase) + (voff)[_i]), (PG8_LAS unsigned*)(lds + (bufoff) + ldsw + _i * 8192), 16, 0, 0); } while (0)
; #define PG8_WAIT_V(n) asm volatile("s_waitcnt vmcnt(" #n ")" ::: "memory")
; template <class Epi, class Sched, bool ALIGN_EPI = false>
; __device__ __forceinline__ void gemm_phase(PG8_LAS unsigned char* lds, const Gemm g, const Sched& S, const Epi& E) {
;     ...
;             PG8_LDB(B0, 1, 0); PG8_LDB(B1, 1, 1); PG8_SCHED; PG8_LDA(At, 1, 0); PG8_STAGE(PG8_SA(0, 1), a2 + hstepA, voffA);
;             PG8_WAIT_V(8); PG8_WAIT_L(0); PG8_BAR; PG8_MMA(0, 0, At, B0); PG8_MMA(0, 1, At, B1); PG8_BAR; PG8_SCHED;
;             PG8_LDA(At, 1, 1); PG8_STAGE(PG8_SB(1, 0), b3, voffB); PG8_STAGE(PG8_SB(1, 1), b3 + hstepB, voffB); PG8_STAGE(PG8_SA(1, 0), a3, voffA);
;             PG8_WAIT_V(8); PG8_WAIT_L(0); PG8_BAR; PG8_MMA(1, 0, At, B0); PG8_MMA(1, 1, At, B1); PG8_BAR; PG8_SCHED;
.Lcy2_1j:
	s_barrier
	s_add_i32 s88, 0, 0x18000
	v_add_u32_e32 v146, s88, v164
	s_add_i32 s89, 0, 0x1c000
	ds_read_b128 v[130:133], v146
	ds_read_b128 v[134:137], v146 offset:1024
	ds_read_b128 v[158:161], v146 offset:2048
	ds_read_b128 v[170:173], v146 offset:3072
	v_add_u32_e32 v146, s89, v164
	ds_read_b128 v[174:177], v146
	ds_read_b128 v[178:181], v146 offset:1024
	ds_read_b128 v[182:185], v146 offset:2048
	ds_read_b128 v[186:189], v146 offset:3072
	s_add_u32 s54, s54, 0x80000
	s_addc_u32 s55, s55, 0
	s_mov_b32 m0, s63
	ds_read_b128 v[190:193], v167 offset:32768
	ds_read_b128 v[194:197], v167 offset:33792
	ds_read_b128 v[198:201], v167 offset:34816
	ds_read_b128 v[202:205], v167 offset:35840
	ds_read_b128 v[206:209], v167 offset:36864
	ds_read_b128 v[210:213], v167 offset:37888
	ds_read_b128 v[214:217], v167 offset:38912
	ds_read_b128 v[218:221], v167 offset:39936
	global_load_lds_dwordx4 v138, s[54:55]
	s_mov_b32 m0, s64
	s_nop 0
	global_load_lds_dwordx4 v142, s[54:55]
	s_waitcnt vmcnt(8)
	s_waitcnt lgkmcnt(0)
	s_barrier
	s_waitcnt lgkmcnt(0)
	v_mfma_f32_16x16x32_bf16 v[126:129], v[130:133], v[190:193], v[126:129]
	v_mfma_f32_16x16x32_bf16 v[122:125], v[158:161], v[190:193], v[122:125]
	v_mfma_f32_16x16x32_bf16 v[114:117], v[130:133], v[198:201], v[114:117]
	v_mfma_f32_16x16x32_bf16 v[106:109], v[158:161], v[198:201], v[106:109]
	v_mfma_f32_16x16x32_bf16 v[98:101], v[130:133], v[206:209], v[98:101]
	v_mfma_f32_16x16x32_bf16 v[90:93], v[158:161], v[206:209], v[90:93]
	v_mfma_f32_16x16x32_bf16 v[82:85], v[130:133], v[214:217], v[82:85]
	v_mfma_f32_16x16x32_bf16 v[74:77], v[158:161], v[214:217], v[74:77]
	v_mfma_f32_16x16x32_bf16 v[126:129], v[134:137], v[194:197], v[126:129]
	v_mfma_f32_16x16x32_bf16 v[122:125], v[170:173], v[194:197], v[122:125]
	v_mfma_f32_16x16x32_bf16 v[114:117], v[134:137], v[202:205], v[114:117]
	v_mfma_f32_16x16x32_bf16 v[106:109], v[170:173], v[202:205], v[106:109]
	v_mfma_f32_16x16x32_bf16 v[98:101], v[134:137], v[210:213], v[98:101]
	v_mfma_f32_16x16x32_bf16 v[90:93], v[170:173], v[210:213], v[90:93]
	v_mfma_f32_16x16x32_bf16 v[82:85], v[134:137], v[218:221], v[82:85]
	v_mfma_f32_16x16x32_bf16 v[74:77], v[170:173], v[218:221], v[74:77]
	v_mfma_f32_16x16x32_bf16 v[118:121], v[174:177], v[190:193], v[118:121]
	v_mfma_f32_16x16x32_bf16 v[110:113], v[182:185], v[190:193], v[110:113]
	v_mfma_f32_16x16x32_bf16 v[102:105], v[174:177], v[198:201], v[102:105]
	v_mfma_f32_16x16x32_bf16 v[94:97], v[182:185], v[198:201], v[94:97]
	v_mfma_f32_16x16x32_bf16 v[86:89], v[174:177], v[206:209], v[86:89]
	v_mfma_f32_16x16x32_bf16 v[78:81], v[182:185], v[206:209], v[78:81]
	v_mfma_f32_16x16x32_bf16 v[70:73], v[174:177], v[214:217], v[70:73]
	v_mfma_f32_16x16x32_bf16 v[66:69], v[182:185], v[214:217], v[66:69]
	v_mfma_f32_16x16x32_bf16 v[118:121], v[178:181], v[194:197], v[118:121]
	v_mfma_f32_16x16x32_bf16 v[110:113], v[186:189], v[194:197], v[110:113]
	v_mfma_f32_16x16x32_bf16 v[102:105], v[178:181], v[202:205], v[102:105]
	v_mfma_f32_16x16x32_bf16 v[94:97], v[186:189], v[202:205], v[94:97]
	v_mfma_f32_16x16x32_bf16 v[86:89], v[178:181], v[210:213], v[86:89]
	v_mfma_f32_16x16x32_bf16 v[78:81], v[186:189], v[210:213], v[78:81]
	v_mfma_f32_16x16x32_bf16 v[70:73], v[178:181], v[218:221], v[70:73]
	v_mfma_f32_16x16x32_bf16 v[66:69], v[186:189], v[218:221], v[66:69]
	s_barrier
	s_add_i32 s101, s88, s58
	s_add_u32 s98, s34, s10
	s_addc_u32 s99, s35, s11
	s_mov_b32 m0, s101
	ds_read_b128 v[190:193], v167 offset:49152
	ds_read_b128 v[194:197], v167 offset:50176
	ds_read_b128 v[198:201], v167 offset:51200
	ds_read_b128 v[202:205], v167 offset:52224
	ds_read_b128 v[206:209], v167 offset:53248
	ds_read_b128 v[210:213], v167 offset:54272
	ds_read_b128 v[214:217], v167 offset:55296
	ds_read_b128 v[218:221], v167 offset:56320
	global_load_lds_dwordx4 v140, s[98:99]
	s_add_i32 m0, s101, 0x2000
	s_add_u32 s34, s34, 0x80080
	s_addc_u32 s35, s35, 0
	s_add_i32 s101, s89, s58
	global_load_lds_dwordx4 v144, s[98:99]
	s_add_u32 s98, s54, s10
	s_addc_u32 s99, s55, s11
	s_sub_u32 s98, s98, 0x80000
	s_subb_u32 s99, s99, 0
	s_mov_b32 m0, s101
	s_nop 0
	global_load_lds_dwordx4 v140, s[34:35]
	s_add_i32 m0, s101, 0x2000
	s_nop 0
	global_load_lds_dwordx4 v144, s[34:35]
	s_mov_b32 m0, s70
	s_nop 0
	global_load_lds_dwordx4 v138, s[98:99]
	s_mov_b32 m0, s71
	s_nop 0
	global_load_lds_dwordx4 v142, s[98:99]
	s_waitcnt vmcnt(8)
	s_waitcnt lgkmcnt(0)
	s_barrier
	s_waitcnt lgkmcnt(0)
	v_mfma_f32_16x16x32_bf16 v[62:65], v[130:133], v[190:193], v[62:65]
	v_mfma_f32_16x16x32_bf16 v[58:61], v[158:161], v[190:193], v[58:61]
	v_mfma_f32_16x16x32_bf16 v[54:57], v[130:133], v[198:201], v[54:57]
	v_mfma_f32_16x16x32_bf16 v[46:49], v[158:161], v[198:201], v[46:49]
	v_mfma_f32_16x16x32_bf16 v[38:41], v[130:133], v[206:209], v[38:41]
	v_mfma_f32_16x16x32_bf16 v[30:33], v[158:161], v[206:209], v[30:33]
	v_mfma_f32_16x16x32_bf16 v[22:25], v[130:133], v[214:217], v[22:25]
	v_mfma_f32_16x16x32_bf16 v[14:17], v[158:161], v[214:217], v[14:17]
	v_mfma_f32_16x16x32_bf16 v[62:65], v[134:137], v[194:197], v[62:65]
	v_mfma_f32_16x16x32_bf16 v[58:61], v[170:173], v[194:197], v[58:61]
	v_mfma_f32_16x16x32_bf16 v[54:57], v[134:137], v[202:205], v[54:57]
	v_mfma_f32_16x16x32_bf16 v[46:49], v[170:173], v[202:205], v[46:49]
	v_mfma_f32_16x16x32_bf16 v[38:41], v[134:137], v[210:213], v[38:41]
	v_mfma_f32_16x16x32_bf16 v[30:33], v[170:173], v[210:213], v[30:33]
	v_mfma_f32_16x16x32_bf16 v[22:25], v[134:137], v[218:221], v[22:25]
	v_mfma_f32_16x16x32_bf16 v[14:17], v[170:173], v[218:221], v[14:17]
	v_mfma_f32_16x16x32_bf16 v[50:53], v[174:177], v[190:193], v[50:53]
	v_mfma_f32_16x16x32_bf16 v[42:45], v[182:185], v[190:193], v[42:45]
	v_mfma_f32_16x16x32_bf16 v[34:37], v[174:177], v[198:201], v[34:37]
	v_mfma_f32_16x16x32_bf16 v[26:29], v[182:185], v[198:201], v[26:29]
	v_mfma_f32_16x16x32_bf16 v[18:21], v[174:177], v[206:209], v[18:21]
	v_mfma_f32_16x16x32_bf16 v[10:13], v[182:185], v[206:209], v[10:13]
	v_mfma_f32_16x16x32_bf16 v[6:9], v[174:177], v[214:217], v[6:9]
	v_mfma_f32_16x16x32_bf16 v[2:5], v[182:185], v[214:217], v[2:5]
	v_mfma_f32_16x16x32_bf16 v[50:53], v[178:181], v[194:197], v[50:53]
	v_mfma_f32_16x16x32_bf16 v[42:45], v[186:189], v[194:197], v[42:45]
	v_mfma_f32_16x16x32_bf16 v[34:37], v[178:181], v[202:205], v[34:37]
	v_mfma_f32_16x16x32_bf16 v[26:29], v[186:189], v[202:205], v[26:29]
	v_mfma_f32_16x16x32_bf16 v[18:21], v[178:181], v[210:213], v[18:21]
	v_mfma_f32_16x16x32_bf16 v[10:13], v[186:189], v[210:213], v[10:13]
	v_mfma_f32_16x16x32_bf16 v[6:9], v[178:181], v[218:221], v[6:9]
	v_mfma_f32_16x16x32_bf16 v[2:5], v[186:189], v[218:221], v[2:5]
	s_barrier
	s_add_i32 s85, s85, 2
	s_add_u32 s52, s52, 0x100
	s_addc_u32 s53, s53, 0
	s_add_u32 s83, s83, 0x100
	s_addc_u32 s84, s84, 0
	s_cmp_gt_u32 s85, 29
	s_cbranch_scc0 .LBB0_734
	s_and_b64 vcc, exec, s[14:15]
	s_cbranch_vccz .LBB0_737
	s_barrier
